# final RMSNorm fast path: straight-line 16 rows/wave, 4 rows in flight, loads before stores, coalesced lane mapping (on top of v48)
# speedup vs baseline: 1.0126x; 1.0033x over previous
.LBB0_1343:
	v_readlane_b32 s2, v253, 34
	v_readlane_b32 s3, v253, 35
	v_readlane_b32 s20, v253, 20
	s_mov_b64 s[0:1], s[76:77]
	s_and_b64 vcc, exec, s[2:3]
	v_readlane_b32 s21, v253, 21
	s_cbranch_vccz .LBB0_1346
	v_lshlrev_b32_e32 v0, 2, v239
	v_readlane_b32 s4, v253, 2
	v_ashrrev_i32_e32 v1, 31, v0
	v_readlane_b32 s12, v253, 10
	v_readlane_b32 s13, v253, 11
	v_readlane_b32 s14, v253, 12
	v_readlane_b32 s15, v253, 13
	v_readlane_b32 s16, v253, 14
	v_readlane_b32 s17, v253, 15
	v_lshlrev_b64 v[16:17], 4, v[0:1]
	v_readlane_b32 s18, v253, 16
	v_readlane_b32 s19, v253, 17
	s_mov_b64 s[12:13], s[16:17]
	v_lshl_add_u64 v[18:19], s[12:13], 0, v[16:17]
	global_load_dwordx4 v[0:3], v[18:19], off offset:48
	global_load_dwordx4 v[4:7], v[18:19], off offset:32
	global_load_dwordx4 v[8:11], v[18:19], off offset:16
	global_load_dwordx4 v[12:15], v[18:19], off
	s_lshl_b64 s[2:3], s[20:21], 6
	s_add_u32 s0, s0, s2
	s_addc_u32 s1, s1, s3
	v_readlane_b32 s5, v253, 3
	s_add_u32 s0, s0, 0x1b400000
	s_mov_b64 s[14:15], s[18:19]
	s_addc_u32 s1, s1, 0
	s_lshl_b64 s[2:3], s[58:59], 6
	s_lshl_b64 s[4:5], s[20:21], 12
	s_add_u32 s4, s14, s4
	v_readlane_b32 s6, v253, 4
	v_readlane_b32 s7, v253, 5
	s_addc_u32 s5, s15, s5
	v_lshl_add_u64 v[16:17], s[4:5], 0, v[16:17]
	s_lshl_b64 s[4:5], s[58:59], 12
	s_lshl_b64 s[6:7], s[20:21], 11
	v_lshlrev_b32_e32 v18, 1, v239
	s_add_u32 s6, s76, s6
	v_ashrrev_i32_e32 v19, 31, v18
	s_addc_u32 s7, s77, s7
	v_lshl_add_u64 v[18:19], v[18:19], 4, s[6:7]
	s_mov_b64 s[6:7], 0x6000010
	v_lshl_add_u64 v[18:19], v[18:19], 0, s[6:7]
	s_lshl_b64 s[6:7], s[58:59], 11
	v_mov_b32_e32 v20, 0
	v_mov_b32_e32 v21, 0x358637bd
	v_readlane_b32 s8, v253, 6
	v_readlane_b32 s9, v253, 7
	v_readlane_b32 s10, v253, 8
	v_readlane_b32 s11, v253, 9
	s_cmpk_lg_u32 s58, 0x800
	s_cbranch_scc1 .LBB0_1345
	v_lshlrev_b32_e32 v60, 4, v239
	v_lshlrev_b32_e32 v61, 3, v239
	s_lshl_b64 s[22:23], s[20:21], 11
	s_add_u32 s22, s76, s22
	s_addc_u32 s23, s77, s23
	s_add_u32 s22, s22, 0x6000000
	s_addc_u32 s23, s23, 0
	s_lshl_b64 s[24:25], s[20:21], 12
	s_add_u32 s24, s14, s24
	s_addc_u32 s25, s15, s25
	global_load_dwordx4 v[64:67], v60, s[12:13]
	global_load_dwordx4 v[68:71], v60, s[12:13] offset:1024
	global_load_dwordx4 v[72:75], v60, s[12:13] offset:2048
	global_load_dwordx4 v[76:79], v60, s[12:13] offset:3072
	global_load_dwordx4 v[80:83], v20, s[0:1]
	global_load_dwordx4 v[84:87], v20, s[0:1] offset:16
	global_load_dwordx4 v[88:91], v20, s[0:1] offset:32
	global_load_dwordx4 v[92:95], v20, s[0:1] offset:48
	global_load_dwordx2 v[96:97], v61, s[22:23]
	global_load_dwordx2 v[98:99], v61, s[22:23] offset:512
	global_load_dwordx2 v[100:101], v61, s[22:23] offset:1024
	global_load_dwordx2 v[102:103], v61, s[22:23] offset:1536
	s_add_u32 s0, s0, s2
	s_addc_u32 s1, s1, s3
	s_add_u32 s22, s22, s6
	s_addc_u32 s23, s23, s7
	global_load_dwordx4 v[104:107], v20, s[0:1]
	global_load_dwordx4 v[108:111], v20, s[0:1] offset:16
	global_load_dwordx4 v[112:115], v20, s[0:1] offset:32
	global_load_dwordx4 v[116:119], v20, s[0:1] offset:48
	global_load_dwordx2 v[120:121], v61, s[22:23]
	global_load_dwordx2 v[122:123], v61, s[22:23] offset:512
	global_load_dwordx2 v[124:125], v61, s[22:23] offset:1024
	global_load_dwordx2 v[126:127], v61, s[22:23] offset:1536
	s_add_u32 s0, s0, s2
	s_addc_u32 s1, s1, s3
	s_add_u32 s22, s22, s6
	s_addc_u32 s23, s23, s7
	global_load_dwordx4 v[128:131], v20, s[0:1]
	global_load_dwordx4 v[132:135], v20, s[0:1] offset:16
	global_load_dwordx4 v[136:139], v20, s[0:1] offset:32
	global_load_dwordx4 v[140:143], v20, s[0:1] offset:48
	global_load_dwordx2 v[144:145], v61, s[22:23]
	global_load_dwordx2 v[146:147], v61, s[22:23] offset:512
	global_load_dwordx2 v[148:149], v61, s[22:23] offset:1024
	global_load_dwordx2 v[150:151], v61, s[22:23] offset:1536
	s_add_u32 s0, s0, s2
	s_addc_u32 s1, s1, s3
	s_add_u32 s22, s22, s6
	s_addc_u32 s23, s23, s7
	global_load_dwordx4 v[152:155], v20, s[0:1]
	global_load_dwordx4 v[156:159], v20, s[0:1] offset:16
	global_load_dwordx4 v[160:163], v20, s[0:1] offset:32
	global_load_dwordx4 v[164:167], v20, s[0:1] offset:48
	global_load_dwordx2 v[168:169], v61, s[22:23]
	global_load_dwordx2 v[170:171], v61, s[22:23] offset:512
	global_load_dwordx2 v[172:173], v61, s[22:23] offset:1024
	global_load_dwordx2 v[174:175], v61, s[22:23] offset:1536
	s_add_u32 s0, s0, s2
	s_addc_u32 s1, s1, s3
	s_add_u32 s22, s22, s6
	s_addc_u32 s23, s23, s7
	s_waitcnt vmcnt(24)
	v_add_f32_e32 v208, v80, v81
	v_add_f32_e32 v209, v82, v83
	v_add_f32_e32 v210, v84, v85
	v_add_f32_e32 v211, v86, v87
	v_add_f32_e32 v212, v88, v89
	v_add_f32_e32 v213, v90, v91
	v_add_f32_e32 v214, v92, v93
	v_add_f32_e32 v215, v94, v95
	v_add_f32_e32 v208, v208, v209
	v_add_f32_e32 v210, v210, v211
	v_add_f32_e32 v212, v212, v213
	v_add_f32_e32 v214, v214, v215
	v_add_f32_e32 v208, v208, v210
	v_add_f32_e32 v212, v212, v214
	v_add_f32_e32 v208, v208, v212
	v_fmamk_f32 v208, v208, 0x3a800000, v21
	v_rsq_f32_e32 v208, v208
	v_lshlrev_b32_e32 v176, 16, v96
	v_and_b32_e32 v177, 0xffff0000, v96
	v_lshlrev_b32_e32 v178, 16, v97
	v_and_b32_e32 v179, 0xffff0000, v97
	v_lshlrev_b32_e32 v180, 16, v98
	v_and_b32_e32 v181, 0xffff0000, v98
	v_lshlrev_b32_e32 v182, 16, v99
	v_and_b32_e32 v183, 0xffff0000, v99
	v_lshlrev_b32_e32 v184, 16, v100
	v_and_b32_e32 v185, 0xffff0000, v100
	v_lshlrev_b32_e32 v186, 16, v101
	v_and_b32_e32 v187, 0xffff0000, v101
	v_lshlrev_b32_e32 v188, 16, v102
	v_and_b32_e32 v189, 0xffff0000, v102
	v_lshlrev_b32_e32 v190, 16, v103
	v_and_b32_e32 v191, 0xffff0000, v103
	v_pk_mul_f32 v[176:177], v[208:209], v[176:177] op_sel_hi:[0,1]
	v_pk_mul_f32 v[178:179], v[208:209], v[178:179] op_sel_hi:[0,1]
	v_pk_mul_f32 v[180:181], v[208:209], v[180:181] op_sel_hi:[0,1]
	v_pk_mul_f32 v[182:183], v[208:209], v[182:183] op_sel_hi:[0,1]
	v_pk_mul_f32 v[184:185], v[208:209], v[184:185] op_sel_hi:[0,1]
	v_pk_mul_f32 v[186:187], v[208:209], v[186:187] op_sel_hi:[0,1]
	v_pk_mul_f32 v[188:189], v[208:209], v[188:189] op_sel_hi:[0,1]
	v_pk_mul_f32 v[190:191], v[208:209], v[190:191] op_sel_hi:[0,1]
	v_pk_mul_f32 v[176:177], v[64:65], v[176:177]
	v_pk_mul_f32 v[178:179], v[66:67], v[178:179]
	v_pk_mul_f32 v[180:181], v[68:69], v[180:181]
	v_pk_mul_f32 v[182:183], v[70:71], v[182:183]
	v_pk_mul_f32 v[184:185], v[72:73], v[184:185]
	v_pk_mul_f32 v[186:187], v[74:75], v[186:187]
	v_pk_mul_f32 v[188:189], v[76:77], v[188:189]
	v_pk_mul_f32 v[190:191], v[78:79], v[190:191]
	global_load_dwordx4 v[80:83], v20, s[0:1]
	global_load_dwordx4 v[84:87], v20, s[0:1] offset:16
	global_load_dwordx4 v[88:91], v20, s[0:1] offset:32
	global_load_dwordx4 v[92:95], v20, s[0:1] offset:48
	global_load_dwordx2 v[96:97], v61, s[22:23]
	global_load_dwordx2 v[98:99], v61, s[22:23] offset:512
	global_load_dwordx2 v[100:101], v61, s[22:23] offset:1024
	global_load_dwordx2 v[102:103], v61, s[22:23] offset:1536
	s_add_u32 s0, s0, s2
	s_addc_u32 s1, s1, s3
	s_add_u32 s22, s22, s6
	s_addc_u32 s23, s23, s7
	global_store_dwordx4 v60, v[176:179], s[24:25]
	global_store_dwordx4 v60, v[180:183], s[24:25] offset:1024
	global_store_dwordx4 v60, v[184:187], s[24:25] offset:2048
	global_store_dwordx4 v60, v[188:191], s[24:25] offset:3072
	s_add_u32 s24, s24, s4
	s_addc_u32 s25, s25, s5
	s_waitcnt vmcnt(28)
	v_add_f32_e32 v208, v104, v105
	v_add_f32_e32 v209, v106, v107
	v_add_f32_e32 v210, v108, v109
	v_add_f32_e32 v211, v110, v111
	v_add_f32_e32 v212, v112, v113
	v_add_f32_e32 v213, v114, v115
	v_add_f32_e32 v214, v116, v117
	v_add_f32_e32 v215, v118, v119
	v_add_f32_e32 v208, v208, v209
	v_add_f32_e32 v210, v210, v211
	v_add_f32_e32 v212, v212, v213
	v_add_f32_e32 v214, v214, v215
	v_add_f32_e32 v208, v208, v210
	v_add_f32_e32 v212, v212, v214
	v_add_f32_e32 v208, v208, v212
	v_fmamk_f32 v208, v208, 0x3a800000, v21
	v_rsq_f32_e32 v208, v208
	v_lshlrev_b32_e32 v192, 16, v120
	v_and_b32_e32 v193, 0xffff0000, v120
	v_lshlrev_b32_e32 v194, 16, v121
	v_and_b32_e32 v195, 0xffff0000, v121
	v_lshlrev_b32_e32 v196, 16, v122
	v_and_b32_e32 v197, 0xffff0000, v122
	v_lshlrev_b32_e32 v198, 16, v123
	v_and_b32_e32 v199, 0xffff0000, v123
	v_lshlrev_b32_e32 v200, 16, v124
	v_and_b32_e32 v201, 0xffff0000, v124
	v_lshlrev_b32_e32 v202, 16, v125
	v_and_b32_e32 v203, 0xffff0000, v125
	v_lshlrev_b32_e32 v204, 16, v126
	v_and_b32_e32 v205, 0xffff0000, v126
	v_lshlrev_b32_e32 v206, 16, v127
	v_and_b32_e32 v207, 0xffff0000, v127
	v_pk_mul_f32 v[192:193], v[208:209], v[192:193] op_sel_hi:[0,1]
	v_pk_mul_f32 v[194:195], v[208:209], v[194:195] op_sel_hi:[0,1]
	v_pk_mul_f32 v[196:197], v[208:209], v[196:197] op_sel_hi:[0,1]
	v_pk_mul_f32 v[198:199], v[208:209], v[198:199] op_sel_hi:[0,1]
	v_pk_mul_f32 v[200:201], v[208:209], v[200:201] op_sel_hi:[0,1]
	v_pk_mul_f32 v[202:203], v[208:209], v[202:203] op_sel_hi:[0,1]
	v_pk_mul_f32 v[204:205], v[208:209], v[204:205] op_sel_hi:[0,1]
	v_pk_mul_f32 v[206:207], v[208:209], v[206:207] op_sel_hi:[0,1]
	v_pk_mul_f32 v[192:193], v[64:65], v[192:193]
	v_pk_mul_f32 v[194:195], v[66:67], v[194:195]
	v_pk_mul_f32 v[196:197], v[68:69], v[196:197]
	v_pk_mul_f32 v[198:199], v[70:71], v[198:199]
	v_pk_mul_f32 v[200:201], v[72:73], v[200:201]
	v_pk_mul_f32 v[202:203], v[74:75], v[202:203]
	v_pk_mul_f32 v[204:205], v[76:77], v[204:205]
	v_pk_mul_f32 v[206:207], v[78:79], v[206:207]
	global_load_dwordx4 v[104:107], v20, s[0:1]
	global_load_dwordx4 v[108:111], v20, s[0:1] offset:16
	global_load_dwordx4 v[112:115], v20, s[0:1] offset:32
	global_load_dwordx4 v[116:119], v20, s[0:1] offset:48
	global_load_dwordx2 v[120:121], v61, s[22:23]
	global_load_dwordx2 v[122:123], v61, s[22:23] offset:512
	global_load_dwordx2 v[124:125], v61, s[22:23] offset:1024
	global_load_dwordx2 v[126:127], v61, s[22:23] offset:1536
	s_add_u32 s0, s0, s2
	s_addc_u32 s1, s1, s3
	s_add_u32 s22, s22, s6
	s_addc_u32 s23, s23, s7
	global_store_dwordx4 v60, v[192:195], s[24:25]
	global_store_dwordx4 v60, v[196:199], s[24:25] offset:1024
	global_store_dwordx4 v60, v[200:203], s[24:25] offset:2048
	global_store_dwordx4 v60, v[204:207], s[24:25] offset:3072
	s_add_u32 s24, s24, s4
	s_addc_u32 s25, s25, s5
	s_waitcnt vmcnt(32)
	v_add_f32_e32 v208, v128, v129
	v_add_f32_e32 v209, v130, v131
	v_add_f32_e32 v210, v132, v133
	v_add_f32_e32 v211, v134, v135
	v_add_f32_e32 v212, v136, v137
	v_add_f32_e32 v213, v138, v139
	v_add_f32_e32 v214, v140, v141
	v_add_f32_e32 v215, v142, v143
	v_add_f32_e32 v208, v208, v209
	v_add_f32_e32 v210, v210, v211
	v_add_f32_e32 v212, v212, v213
	v_add_f32_e32 v214, v214, v215
	v_add_f32_e32 v208, v208, v210
	v_add_f32_e32 v212, v212, v214
	v_add_f32_e32 v208, v208, v212
	v_fmamk_f32 v208, v208, 0x3a800000, v21
	v_rsq_f32_e32 v208, v208
	v_lshlrev_b32_e32 v176, 16, v144
	v_and_b32_e32 v177, 0xffff0000, v144
	v_lshlrev_b32_e32 v178, 16, v145
	v_and_b32_e32 v179, 0xffff0000, v145
	v_lshlrev_b32_e32 v180, 16, v146
	v_and_b32_e32 v181, 0xffff0000, v146
	v_lshlrev_b32_e32 v182, 16, v147
	v_and_b32_e32 v183, 0xffff0000, v147
	v_lshlrev_b32_e32 v184, 16, v148
	v_and_b32_e32 v185, 0xffff0000, v148
	v_lshlrev_b32_e32 v186, 16, v149
	v_and_b32_e32 v187, 0xffff0000, v149
	v_lshlrev_b32_e32 v188, 16, v150
	v_and_b32_e32 v189, 0xffff0000, v150
	v_lshlrev_b32_e32 v190, 16, v151
	v_and_b32_e32 v191, 0xffff0000, v151
	v_pk_mul_f32 v[176:177], v[208:209], v[176:177] op_sel_hi:[0,1]
	v_pk_mul_f32 v[178:179], v[208:209], v[178:179] op_sel_hi:[0,1]
	v_pk_mul_f32 v[180:181], v[208:209], v[180:181] op_sel_hi:[0,1]
	v_pk_mul_f32 v[182:183], v[208:209], v[182:183] op_sel_hi:[0,1]
	v_pk_mul_f32 v[184:185], v[208:209], v[184:185] op_sel_hi:[0,1]
	v_pk_mul_f32 v[186:187], v[208:209], v[186:187] op_sel_hi:[0,1]
	v_pk_mul_f32 v[188:189], v[208:209], v[188:189] op_sel_hi:[0,1]
	v_pk_mul_f32 v[190:191], v[208:209], v[190:191] op_sel_hi:[0,1]
	v_pk_mul_f32 v[176:177], v[64:65], v[176:177]
	v_pk_mul_f32 v[178:179], v[66:67], v[178:179]
	v_pk_mul_f32 v[180:181], v[68:69], v[180:181]
	v_pk_mul_f32 v[182:183], v[70:71], v[182:183]
	v_pk_mul_f32 v[184:185], v[72:73], v[184:185]
	v_pk_mul_f32 v[186:187], v[74:75], v[186:187]
	v_pk_mul_f32 v[188:189], v[76:77], v[188:189]
	v_pk_mul_f32 v[190:191], v[78:79], v[190:191]
	global_load_dwordx4 v[128:131], v20, s[0:1]
	global_load_dwordx4 v[132:135], v20, s[0:1] offset:16
	global_load_dwordx4 v[136:139], v20, s[0:1] offset:32
	global_load_dwordx4 v[140:143], v20, s[0:1] offset:48
	global_load_dwordx2 v[144:145], v61, s[22:23]
	global_load_dwordx2 v[146:147], v61, s[22:23] offset:512
	global_load_dwordx2 v[148:149], v61, s[22:23] offset:1024
	global_load_dwordx2 v[150:151], v61, s[22:23] offset:1536
	s_add_u32 s0, s0, s2
	s_addc_u32 s1, s1, s3
	s_add_u32 s22, s22, s6
	s_addc_u32 s23, s23, s7
	global_store_dwordx4 v60, v[176:179], s[24:25]
	global_store_dwordx4 v60, v[180:183], s[24:25] offset:1024
	global_store_dwordx4 v60, v[184:187], s[24:25] offset:2048
	global_store_dwordx4 v60, v[188:191], s[24:25] offset:3072
	s_add_u32 s24, s24, s4
	s_addc_u32 s25, s25, s5
	s_waitcnt vmcnt(36)
	v_add_f32_e32 v208, v152, v153
	v_add_f32_e32 v209, v154, v155
	v_add_f32_e32 v210, v156, v157
	v_add_f32_e32 v211, v158, v159
	v_add_f32_e32 v212, v160, v161
	v_add_f32_e32 v213, v162, v163
	v_add_f32_e32 v214, v164, v165
	v_add_f32_e32 v215, v166, v167
	v_add_f32_e32 v208, v208, v209
	v_add_f32_e32 v210, v210, v211
	v_add_f32_e32 v212, v212, v213
	v_add_f32_e32 v214, v214, v215
	v_add_f32_e32 v208, v208, v210
	v_add_f32_e32 v212, v212, v214
	v_add_f32_e32 v208, v208, v212
	v_fmamk_f32 v208, v208, 0x3a800000, v21
	v_rsq_f32_e32 v208, v208
	v_lshlrev_b32_e32 v192, 16, v168
	v_and_b32_e32 v193, 0xffff0000, v168
	v_lshlrev_b32_e32 v194, 16, v169
	v_and_b32_e32 v195, 0xffff0000, v169
	v_lshlrev_b32_e32 v196, 16, v170
	v_and_b32_e32 v197, 0xffff0000, v170
	v_lshlrev_b32_e32 v198, 16, v171
	v_and_b32_e32 v199, 0xffff0000, v171
	v_lshlrev_b32_e32 v200, 16, v172
	v_and_b32_e32 v201, 0xffff0000, v172
	v_lshlrev_b32_e32 v202, 16, v173
	v_and_b32_e32 v203, 0xffff0000, v173
	v_lshlrev_b32_e32 v204, 16, v174
	v_and_b32_e32 v205, 0xffff0000, v174
	v_lshlrev_b32_e32 v206, 16, v175
	v_and_b32_e32 v207, 0xffff0000, v175
	v_pk_mul_f32 v[192:193], v[208:209], v[192:193] op_sel_hi:[0,1]
	v_pk_mul_f32 v[194:195], v[208:209], v[194:195] op_sel_hi:[0,1]
	v_pk_mul_f32 v[196:197], v[208:209], v[196:197] op_sel_hi:[0,1]
	v_pk_mul_f32 v[198:199], v[208:209], v[198:199] op_sel_hi:[0,1]
	v_pk_mul_f32 v[200:201], v[208:209], v[200:201] op_sel_hi:[0,1]
	v_pk_mul_f32 v[202:203], v[208:209], v[202:203] op_sel_hi:[0,1]
	v_pk_mul_f32 v[204:205], v[208:209], v[204:205] op_sel_hi:[0,1]
	v_pk_mul_f32 v[206:207], v[208:209], v[206:207] op_sel_hi:[0,1]
	v_pk_mul_f32 v[192:193], v[64:65], v[192:193]
	v_pk_mul_f32 v[194:195], v[66:67], v[194:195]
	v_pk_mul_f32 v[196:197], v[68:69], v[196:197]
	v_pk_mul_f32 v[198:199], v[70:71], v[198:199]
	v_pk_mul_f32 v[200:201], v[72:73], v[200:201]
	v_pk_mul_f32 v[202:203], v[74:75], v[202:203]
	v_pk_mul_f32 v[204:205], v[76:77], v[204:205]
	v_pk_mul_f32 v[206:207], v[78:79], v[206:207]
	global_load_dwordx4 v[152:155], v20, s[0:1]
	global_load_dwordx4 v[156:159], v20, s[0:1] offset:16
	global_load_dwordx4 v[160:163], v20, s[0:1] offset:32
	global_load_dwordx4 v[164:167], v20, s[0:1] offset:48
	global_load_dwordx2 v[168:169], v61, s[22:23]
	global_load_dwordx2 v[170:171], v61, s[22:23] offset:512
	global_load_dwordx2 v[172:173], v61, s[22:23] offset:1024
	global_load_dwordx2 v[174:175], v61, s[22:23] offset:1536
	s_add_u32 s0, s0, s2
	s_addc_u32 s1, s1, s3
	s_add_u32 s22, s22, s6
	s_addc_u32 s23, s23, s7
	global_store_dwordx4 v60, v[192:195], s[24:25]
	global_store_dwordx4 v60, v[196:199], s[24:25] offset:1024
	global_store_dwordx4 v60, v[200:203], s[24:25] offset:2048
	global_store_dwordx4 v60, v[204:207], s[24:25] offset:3072
	s_add_u32 s24, s24, s4
	s_addc_u32 s25, s25, s5
	s_waitcnt vmcnt(40)
	v_add_f32_e32 v208, v80, v81
	v_add_f32_e32 v209, v82, v83
	v_add_f32_e32 v210, v84, v85
	v_add_f32_e32 v211, v86, v87
	v_add_f32_e32 v212, v88, v89
	v_add_f32_e32 v213, v90, v91
	v_add_f32_e32 v214, v92, v93
	v_add_f32_e32 v215, v94, v95
	v_add_f32_e32 v208, v208, v209
	v_add_f32_e32 v210, v210, v211
	v_add_f32_e32 v212, v212, v213
	v_add_f32_e32 v214, v214, v215
	v_add_f32_e32 v208, v208, v210
	v_add_f32_e32 v212, v212, v214
	v_add_f32_e32 v208, v208, v212
	v_fmamk_f32 v208, v208, 0x3a800000, v21
	v_rsq_f32_e32 v208, v208
	v_lshlrev_b32_e32 v176, 16, v96
	v_and_b32_e32 v177, 0xffff0000, v96
	v_lshlrev_b32_e32 v178, 16, v97
	v_and_b32_e32 v179, 0xffff0000, v97
	v_lshlrev_b32_e32 v180, 16, v98
	v_and_b32_e32 v181, 0xffff0000, v98
	v_lshlrev_b32_e32 v182, 16, v99
	v_and_b32_e32 v183, 0xffff0000, v99
	v_lshlrev_b32_e32 v184, 16, v100
	v_and_b32_e32 v185, 0xffff0000, v100
	v_lshlrev_b32_e32 v186, 16, v101
	v_and_b32_e32 v187, 0xffff0000, v101
	v_lshlrev_b32_e32 v188, 16, v102
	v_and_b32_e32 v189, 0xffff0000, v102
	v_lshlrev_b32_e32 v190, 16, v103
	v_and_b32_e32 v191, 0xffff0000, v103
	v_pk_mul_f32 v[176:177], v[208:209], v[176:177] op_sel_hi:[0,1]
	v_pk_mul_f32 v[178:179], v[208:209], v[178:179] op_sel_hi:[0,1]
	v_pk_mul_f32 v[180:181], v[208:209], v[180:181] op_sel_hi:[0,1]
	v_pk_mul_f32 v[182:183], v[208:209], v[182:183] op_sel_hi:[0,1]
	v_pk_mul_f32 v[184:185], v[208:209], v[184:185] op_sel_hi:[0,1]
	v_pk_mul_f32 v[186:187], v[208:209], v[186:187] op_sel_hi:[0,1]
	v_pk_mul_f32 v[188:189], v[208:209], v[188:189] op_sel_hi:[0,1]
	v_pk_mul_f32 v[190:191], v[208:209], v[190:191] op_sel_hi:[0,1]
	v_pk_mul_f32 v[176:177], v[64:65], v[176:177]
	v_pk_mul_f32 v[178:179], v[66:67], v[178:179]
	v_pk_mul_f32 v[180:181], v[68:69], v[180:181]
	v_pk_mul_f32 v[182:183], v[70:71], v[182:183]
	v_pk_mul_f32 v[184:185], v[72:73], v[184:185]
	v_pk_mul_f32 v[186:187], v[74:75], v[186:187]
	v_pk_mul_f32 v[188:189], v[76:77], v[188:189]
	v_pk_mul_f32 v[190:191], v[78:79], v[190:191]
	global_load_dwordx4 v[80:83], v20, s[0:1]
	global_load_dwordx4 v[84:87], v20, s[0:1] offset:16
	global_load_dwordx4 v[88:91], v20, s[0:1] offset:32
	global_load_dwordx4 v[92:95], v20, s[0:1] offset:48
	global_load_dwordx2 v[96:97], v61, s[22:23]
	global_load_dwordx2 v[98:99], v61, s[22:23] offset:512
	global_load_dwordx2 v[100:101], v61, s[22:23] offset:1024
	global_load_dwordx2 v[102:103], v61, s[22:23] offset:1536
	s_add_u32 s0, s0, s2
	s_addc_u32 s1, s1, s3
	s_add_u32 s22, s22, s6
	s_addc_u32 s23, s23, s7
	global_store_dwordx4 v60, v[176:179], s[24:25]
	global_store_dwordx4 v60, v[180:183], s[24:25] offset:1024
	global_store_dwordx4 v60, v[184:187], s[24:25] offset:2048
	global_store_dwordx4 v60, v[188:191], s[24:25] offset:3072
	s_add_u32 s24, s24, s4
	s_addc_u32 s25, s25, s5
	s_waitcnt vmcnt(40)
	v_add_f32_e32 v208, v104, v105
	v_add_f32_e32 v209, v106, v107
	v_add_f32_e32 v210, v108, v109
	v_add_f32_e32 v211, v110, v111
	v_add_f32_e32 v212, v112, v113
	v_add_f32_e32 v213, v114, v115
	v_add_f32_e32 v214, v116, v117
	v_add_f32_e32 v215, v118, v119
	v_add_f32_e32 v208, v208, v209
	v_add_f32_e32 v210, v210, v211
	v_add_f32_e32 v212, v212, v213
	v_add_f32_e32 v214, v214, v215
	v_add_f32_e32 v208, v208, v210
	v_add_f32_e32 v212, v212, v214
	v_add_f32_e32 v208, v208, v212
	v_fmamk_f32 v208, v208, 0x3a800000, v21
	v_rsq_f32_e32 v208, v208
	v_lshlrev_b32_e32 v192, 16, v120
	v_and_b32_e32 v193, 0xffff0000, v120
	v_lshlrev_b32_e32 v194, 16, v121
	v_and_b32_e32 v195, 0xffff0000, v121
	v_lshlrev_b32_e32 v196, 16, v122
	v_and_b32_e32 v197, 0xffff0000, v122
	v_lshlrev_b32_e32 v198, 16, v123
	v_and_b32_e32 v199, 0xffff0000, v123
	v_lshlrev_b32_e32 v200, 16, v124
	v_and_b32_e32 v201, 0xffff0000, v124
	v_lshlrev_b32_e32 v202, 16, v125
	v_and_b32_e32 v203, 0xffff0000, v125
	v_lshlrev_b32_e32 v204, 16, v126
	v_and_b32_e32 v205, 0xffff0000, v126
	v_lshlrev_b32_e32 v206, 16, v127
	v_and_b32_e32 v207, 0xffff0000, v127
	v_pk_mul_f32 v[192:193], v[208:209], v[192:193] op_sel_hi:[0,1]
	v_pk_mul_f32 v[194:195], v[208:209], v[194:195] op_sel_hi:[0,1]
	v_pk_mul_f32 v[196:197], v[208:209], v[196:197] op_sel_hi:[0,1]
	v_pk_mul_f32 v[198:199], v[208:209], v[198:199] op_sel_hi:[0,1]
	v_pk_mul_f32 v[200:201], v[208:209], v[200:201] op_sel_hi:[0,1]
	v_pk_mul_f32 v[202:203], v[208:209], v[202:203] op_sel_hi:[0,1]
	v_pk_mul_f32 v[204:205], v[208:209], v[204:205] op_sel_hi:[0,1]
	v_pk_mul_f32 v[206:207], v[208:209], v[206:207] op_sel_hi:[0,1]
	v_pk_mul_f32 v[192:193], v[64:65], v[192:193]
	v_pk_mul_f32 v[194:195], v[66:67], v[194:195]
	v_pk_mul_f32 v[196:197], v[68:69], v[196:197]
	v_pk_mul_f32 v[198:199], v[70:71], v[198:199]
	v_pk_mul_f32 v[200:201], v[72:73], v[200:201]
	v_pk_mul_f32 v[202:203], v[74:75], v[202:203]
	v_pk_mul_f32 v[204:205], v[76:77], v[204:205]
	v_pk_mul_f32 v[206:207], v[78:79], v[206:207]
	global_load_dwordx4 v[104:107], v20, s[0:1]
	global_load_dwordx4 v[108:111], v20, s[0:1] offset:16
	global_load_dwordx4 v[112:115], v20, s[0:1] offset:32
	global_load_dwordx4 v[116:119], v20, s[0:1] offset:48
	global_load_dwordx2 v[120:121], v61, s[22:23]
	global_load_dwordx2 v[122:123], v61, s[22:23] offset:512
	global_load_dwordx2 v[124:125], v61, s[22:23] offset:1024
	global_load_dwordx2 v[126:127], v61, s[22:23] offset:1536
	s_add_u32 s0, s0, s2
	s_addc_u32 s1, s1, s3
	s_add_u32 s22, s22, s6
	s_addc_u32 s23, s23, s7
	global_store_dwordx4 v60, v[192:195], s[24:25]
	global_store_dwordx4 v60, v[196:199], s[24:25] offset:1024
	global_store_dwordx4 v60, v[200:203], s[24:25] offset:2048
	global_store_dwordx4 v60, v[204:207], s[24:25] offset:3072
	s_add_u32 s24, s24, s4
	s_addc_u32 s25, s25, s5
	s_waitcnt vmcnt(40)
	v_add_f32_e32 v208, v128, v129
	v_add_f32_e32 v209, v130, v131
	v_add_f32_e32 v210, v132, v133
	v_add_f32_e32 v211, v134, v135
	v_add_f32_e32 v212, v136, v137
	v_add_f32_e32 v213, v138, v139
	v_add_f32_e32 v214, v140, v141
	v_add_f32_e32 v215, v142, v143
	v_add_f32_e32 v208, v208, v209
	v_add_f32_e32 v210, v210, v211
	v_add_f32_e32 v212, v212, v213
	v_add_f32_e32 v214, v214, v215
	v_add_f32_e32 v208, v208, v210
	v_add_f32_e32 v212, v212, v214
	v_add_f32_e32 v208, v208, v212
	v_fmamk_f32 v208, v208, 0x3a800000, v21
	v_rsq_f32_e32 v208, v208
	v_lshlrev_b32_e32 v176, 16, v144
	v_and_b32_e32 v177, 0xffff0000, v144
	v_lshlrev_b32_e32 v178, 16, v145
	v_and_b32_e32 v179, 0xffff0000, v145
	v_lshlrev_b32_e32 v180, 16, v146
	v_and_b32_e32 v181, 0xffff0000, v146
	v_lshlrev_b32_e32 v182, 16, v147
	v_and_b32_e32 v183, 0xffff0000, v147
	v_lshlrev_b32_e32 v184, 16, v148
	v_and_b32_e32 v185, 0xffff0000, v148
	v_lshlrev_b32_e32 v186, 16, v149
	v_and_b32_e32 v187, 0xffff0000, v149
	v_lshlrev_b32_e32 v188, 16, v150
	v_and_b32_e32 v189, 0xffff0000, v150
	v_lshlrev_b32_e32 v190, 16, v151
	v_and_b32_e32 v191, 0xffff0000, v151
	v_pk_mul_f32 v[176:177], v[208:209], v[176:177] op_sel_hi:[0,1]
	v_pk_mul_f32 v[178:179], v[208:209], v[178:179] op_sel_hi:[0,1]
	v_pk_mul_f32 v[180:181], v[208:209], v[180:181] op_sel_hi:[0,1]
	v_pk_mul_f32 v[182:183], v[208:209], v[182:183] op_sel_hi:[0,1]
	v_pk_mul_f32 v[184:185], v[208:209], v[184:185] op_sel_hi:[0,1]
	v_pk_mul_f32 v[186:187], v[208:209], v[186:187] op_sel_hi:[0,1]
	v_pk_mul_f32 v[188:189], v[208:209], v[188:189] op_sel_hi:[0,1]
	v_pk_mul_f32 v[190:191], v[208:209], v[190:191] op_sel_hi:[0,1]
	v_pk_mul_f32 v[176:177], v[64:65], v[176:177]
	v_pk_mul_f32 v[178:179], v[66:67], v[178:179]
	v_pk_mul_f32 v[180:181], v[68:69], v[180:181]
	v_pk_mul_f32 v[182:183], v[70:71], v[182:183]
	v_pk_mul_f32 v[184:185], v[72:73], v[184:185]
	v_pk_mul_f32 v[186:187], v[74:75], v[186:187]
	v_pk_mul_f32 v[188:189], v[76:77], v[188:189]
	v_pk_mul_f32 v[190:191], v[78:79], v[190:191]
	global_load_dwordx4 v[128:131], v20, s[0:1]
	global_load_dwordx4 v[132:135], v20, s[0:1] offset:16
	global_load_dwordx4 v[136:139], v20, s[0:1] offset:32
	global_load_dwordx4 v[140:143], v20, s[0:1] offset:48
	global_load_dwordx2 v[144:145], v61, s[22:23]
	global_load_dwordx2 v[146:147], v61, s[22:23] offset:512
	global_load_dwordx2 v[148:149], v61, s[22:23] offset:1024
	global_load_dwordx2 v[150:151], v61, s[22:23] offset:1536
	s_add_u32 s0, s0, s2
	s_addc_u32 s1, s1, s3
	s_add_u32 s22, s22, s6
	s_addc_u32 s23, s23, s7
	global_store_dwordx4 v60, v[176:179], s[24:25]
	global_store_dwordx4 v60, v[180:183], s[24:25] offset:1024
	global_store_dwordx4 v60, v[184:187], s[24:25] offset:2048
	global_store_dwordx4 v60, v[188:191], s[24:25] offset:3072
	s_add_u32 s24, s24, s4
	s_addc_u32 s25, s25, s5
	s_waitcnt vmcnt(40)
	v_add_f32_e32 v208, v152, v153
	v_add_f32_e32 v209, v154, v155
	v_add_f32_e32 v210, v156, v157
	v_add_f32_e32 v211, v158, v159
	v_add_f32_e32 v212, v160, v161
	v_add_f32_e32 v213, v162, v163
	v_add_f32_e32 v214, v164, v165
	v_add_f32_e32 v215, v166, v167
	v_add_f32_e32 v208, v208, v209
	v_add_f32_e32 v210, v210, v211
	v_add_f32_e32 v212, v212, v213
	v_add_f32_e32 v214, v214, v215
	v_add_f32_e32 v208, v208, v210
	v_add_f32_e32 v212, v212, v214
	v_add_f32_e32 v208, v208, v212
	v_fmamk_f32 v208, v208, 0x3a800000, v21
	v_rsq_f32_e32 v208, v208
	v_lshlrev_b32_e32 v192, 16, v168
	v_and_b32_e32 v193, 0xffff0000, v168
	v_lshlrev_b32_e32 v194, 16, v169
	v_and_b32_e32 v195, 0xffff0000, v169
	v_lshlrev_b32_e32 v196, 16, v170
	v_and_b32_e32 v197, 0xffff0000, v170
	v_lshlrev_b32_e32 v198, 16, v171
	v_and_b32_e32 v199, 0xffff0000, v171
	v_lshlrev_b32_e32 v200, 16, v172
	v_and_b32_e32 v201, 0xffff0000, v172
	v_lshlrev_b32_e32 v202, 16, v173
	v_and_b32_e32 v203, 0xffff0000, v173
	v_lshlrev_b32_e32 v204, 16, v174
	v_and_b32_e32 v205, 0xffff0000, v174
	v_lshlrev_b32_e32 v206, 16, v175
	v_and_b32_e32 v207, 0xffff0000, v175
	v_pk_mul_f32 v[192:193], v[208:209], v[192:193] op_sel_hi:[0,1]
	v_pk_mul_f32 v[194:195], v[208:209], v[194:195] op_sel_hi:[0,1]
	v_pk_mul_f32 v[196:197], v[208:209], v[196:197] op_sel_hi:[0,1]
	v_pk_mul_f32 v[198:199], v[208:209], v[198:199] op_sel_hi:[0,1]
	v_pk_mul_f32 v[200:201], v[208:209], v[200:201] op_sel_hi:[0,1]
	v_pk_mul_f32 v[202:203], v[208:209], v[202:203] op_sel_hi:[0,1]
	v_pk_mul_f32 v[204:205], v[208:209], v[204:205] op_sel_hi:[0,1]
	v_pk_mul_f32 v[206:207], v[208:209], v[206:207] op_sel_hi:[0,1]
	v_pk_mul_f32 v[192:193], v[64:65], v[192:193]
	v_pk_mul_f32 v[194:195], v[66:67], v[194:195]
	v_pk_mul_f32 v[196:197], v[68:69], v[196:197]
	v_pk_mul_f32 v[198:199], v[70:71], v[198:199]
	v_pk_mul_f32 v[200:201], v[72:73], v[200:201]
	v_pk_mul_f32 v[202:203], v[74:75], v[202:203]
	v_pk_mul_f32 v[204:205], v[76:77], v[204:205]
	v_pk_mul_f32 v[206:207], v[78:79], v[206:207]
	global_load_dwordx4 v[152:155], v20, s[0:1]
	global_load_dwordx4 v[156:159], v20, s[0:1] offset:16
	global_load_dwordx4 v[160:163], v20, s[0:1] offset:32
	global_load_dwordx4 v[164:167], v20, s[0:1] offset:48
	global_load_dwordx2 v[168:169], v61, s[22:23]
	global_load_dwordx2 v[170:171], v61, s[22:23] offset:512
	global_load_dwordx2 v[172:173], v61, s[22:23] offset:1024
	global_load_dwordx2 v[174:175], v61, s[22:23] offset:1536
	s_add_u32 s0, s0, s2
	s_addc_u32 s1, s1, s3
	s_add_u32 s22, s22, s6
	s_addc_u32 s23, s23, s7
	global_store_dwordx4 v60, v[192:195], s[24:25]
	global_store_dwordx4 v60, v[196:199], s[24:25] offset:1024
	global_store_dwordx4 v60, v[200:203], s[24:25] offset:2048
	global_store_dwordx4 v60, v[204:207], s[24:25] offset:3072
	s_add_u32 s24, s24, s4
	s_addc_u32 s25, s25, s5
	s_waitcnt vmcnt(40)
	v_add_f32_e32 v208, v80, v81
	v_add_f32_e32 v209, v82, v83
	v_add_f32_e32 v210, v84, v85
	v_add_f32_e32 v211, v86, v87
	v_add_f32_e32 v212, v88, v89
	v_add_f32_e32 v213, v90, v91
	v_add_f32_e32 v214, v92, v93
	v_add_f32_e32 v215, v94, v95
	v_add_f32_e32 v208, v208, v209
	v_add_f32_e32 v210, v210, v211
	v_add_f32_e32 v212, v212, v213
	v_add_f32_e32 v214, v214, v215
	v_add_f32_e32 v208, v208, v210
	v_add_f32_e32 v212, v212, v214
	v_add_f32_e32 v208, v208, v212
	v_fmamk_f32 v208, v208, 0x3a800000, v21
	v_rsq_f32_e32 v208, v208
	v_lshlrev_b32_e32 v176, 16, v96
	v_and_b32_e32 v177, 0xffff0000, v96
	v_lshlrev_b32_e32 v178, 16, v97
	v_and_b32_e32 v179, 0xffff0000, v97
	v_lshlrev_b32_e32 v180, 16, v98
	v_and_b32_e32 v181, 0xffff0000, v98
	v_lshlrev_b32_e32 v182, 16, v99
	v_and_b32_e32 v183, 0xffff0000, v99
	v_lshlrev_b32_e32 v184, 16, v100
	v_and_b32_e32 v185, 0xffff0000, v100
	v_lshlrev_b32_e32 v186, 16, v101
	v_and_b32_e32 v187, 0xffff0000, v101
	v_lshlrev_b32_e32 v188, 16, v102
	v_and_b32_e32 v189, 0xffff0000, v102
	v_lshlrev_b32_e32 v190, 16, v103
	v_and_b32_e32 v191, 0xffff0000, v103
	v_pk_mul_f32 v[176:177], v[208:209], v[176:177] op_sel_hi:[0,1]
	v_pk_mul_f32 v[178:179], v[208:209], v[178:179] op_sel_hi:[0,1]
	v_pk_mul_f32 v[180:181], v[208:209], v[180:181] op_sel_hi:[0,1]
	v_pk_mul_f32 v[182:183], v[208:209], v[182:183] op_sel_hi:[0,1]
	v_pk_mul_f32 v[184:185], v[208:209], v[184:185] op_sel_hi:[0,1]
	v_pk_mul_f32 v[186:187], v[208:209], v[186:187] op_sel_hi:[0,1]
	v_pk_mul_f32 v[188:189], v[208:209], v[188:189] op_sel_hi:[0,1]
	v_pk_mul_f32 v[190:191], v[208:209], v[190:191] op_sel_hi:[0,1]
	v_pk_mul_f32 v[176:177], v[64:65], v[176:177]
	v_pk_mul_f32 v[178:179], v[66:67], v[178:179]
	v_pk_mul_f32 v[180:181], v[68:69], v[180:181]
	v_pk_mul_f32 v[182:183], v[70:71], v[182:183]
	v_pk_mul_f32 v[184:185], v[72:73], v[184:185]
	v_pk_mul_f32 v[186:187], v[74:75], v[186:187]
	v_pk_mul_f32 v[188:189], v[76:77], v[188:189]
	v_pk_mul_f32 v[190:191], v[78:79], v[190:191]
	global_load_dwordx4 v[80:83], v20, s[0:1]
	global_load_dwordx4 v[84:87], v20, s[0:1] offset:16
	global_load_dwordx4 v[88:91], v20, s[0:1] offset:32
	global_load_dwordx4 v[92:95], v20, s[0:1] offset:48
	global_load_dwordx2 v[96:97], v61, s[22:23]
	global_load_dwordx2 v[98:99], v61, s[22:23] offset:512
	global_load_dwordx2 v[100:101], v61, s[22:23] offset:1024
	global_load_dwordx2 v[102:103], v61, s[22:23] offset:1536
	s_add_u32 s0, s0, s2
	s_addc_u32 s1, s1, s3
	s_add_u32 s22, s22, s6
	s_addc_u32 s23, s23, s7
	global_store_dwordx4 v60, v[176:179], s[24:25]
	global_store_dwordx4 v60, v[180:183], s[24:25] offset:1024
	global_store_dwordx4 v60, v[184:187], s[24:25] offset:2048
	global_store_dwordx4 v60, v[188:191], s[24:25] offset:3072
	s_add_u32 s24, s24, s4
	s_addc_u32 s25, s25, s5
	s_waitcnt vmcnt(40)
	v_add_f32_e32 v208, v104, v105
	v_add_f32_e32 v209, v106, v107
	v_add_f32_e32 v210, v108, v109
	v_add_f32_e32 v211, v110, v111
	v_add_f32_e32 v212, v112, v113
	v_add_f32_e32 v213, v114, v115
	v_add_f32_e32 v214, v116, v117
	v_add_f32_e32 v215, v118, v119
	v_add_f32_e32 v208, v208, v209
	v_add_f32_e32 v210, v210, v211
	v_add_f32_e32 v212, v212, v213
	v_add_f32_e32 v214, v214, v215
	v_add_f32_e32 v208, v208, v210
	v_add_f32_e32 v212, v212, v214
	v_add_f32_e32 v208, v208, v212
	v_fmamk_f32 v208, v208, 0x3a800000, v21
	v_rsq_f32_e32 v208, v208
	v_lshlrev_b32_e32 v192, 16, v120
	v_and_b32_e32 v193, 0xffff0000, v120
	v_lshlrev_b32_e32 v194, 16, v121
	v_and_b32_e32 v195, 0xffff0000, v121
	v_lshlrev_b32_e32 v196, 16, v122
	v_and_b32_e32 v197, 0xffff0000, v122
	v_lshlrev_b32_e32 v198, 16, v123
	v_and_b32_e32 v199, 0xffff0000, v123
	v_lshlrev_b32_e32 v200, 16, v124
	v_and_b32_e32 v201, 0xffff0000, v124
	v_lshlrev_b32_e32 v202, 16, v125
	v_and_b32_e32 v203, 0xffff0000, v125
	v_lshlrev_b32_e32 v204, 16, v126
	v_and_b32_e32 v205, 0xffff0000, v126
	v_lshlrev_b32_e32 v206, 16, v127
	v_and_b32_e32 v207, 0xffff0000, v127
	v_pk_mul_f32 v[192:193], v[208:209], v[192:193] op_sel_hi:[0,1]
	v_pk_mul_f32 v[194:195], v[208:209], v[194:195] op_sel_hi:[0,1]
	v_pk_mul_f32 v[196:197], v[208:209], v[196:197] op_sel_hi:[0,1]
	v_pk_mul_f32 v[198:199], v[208:209], v[198:199] op_sel_hi:[0,1]
	v_pk_mul_f32 v[200:201], v[208:209], v[200:201] op_sel_hi:[0,1]
	v_pk_mul_f32 v[202:203], v[208:209], v[202:203] op_sel_hi:[0,1]
	v_pk_mul_f32 v[204:205], v[208:209], v[204:205] op_sel_hi:[0,1]
	v_pk_mul_f32 v[206:207], v[208:209], v[206:207] op_sel_hi:[0,1]
	v_pk_mul_f32 v[192:193], v[64:65], v[192:193]
	v_pk_mul_f32 v[194:195], v[66:67], v[194:195]
	v_pk_mul_f32 v[196:197], v[68:69], v[196:197]
	v_pk_mul_f32 v[198:199], v[70:71], v[198:199]
	v_pk_mul_f32 v[200:201], v[72:73], v[200:201]
	v_pk_mul_f32 v[202:203], v[74:75], v[202:203]
	v_pk_mul_f32 v[204:205], v[76:77], v[204:205]
	v_pk_mul_f32 v[206:207], v[78:79], v[206:207]
	global_load_dwordx4 v[104:107], v20, s[0:1]
	global_load_dwordx4 v[108:111], v20, s[0:1] offset:16
	global_load_dwordx4 v[112:115], v20, s[0:1] offset:32
	global_load_dwordx4 v[116:119], v20, s[0:1] offset:48
	global_load_dwordx2 v[120:121], v61, s[22:23]
	global_load_dwordx2 v[122:123], v61, s[22:23] offset:512
	global_load_dwordx2 v[124:125], v61, s[22:23] offset:1024
	global_load_dwordx2 v[126:127], v61, s[22:23] offset:1536
	s_add_u32 s0, s0, s2
	s_addc_u32 s1, s1, s3
	s_add_u32 s22, s22, s6
	s_addc_u32 s23, s23, s7
	global_store_dwordx4 v60, v[192:195], s[24:25]
	global_store_dwordx4 v60, v[196:199], s[24:25] offset:1024
	global_store_dwordx4 v60, v[200:203], s[24:25] offset:2048
	global_store_dwordx4 v60, v[204:207], s[24:25] offset:3072
	s_add_u32 s24, s24, s4
	s_addc_u32 s25, s25, s5
	s_waitcnt vmcnt(40)
	v_add_f32_e32 v208, v128, v129
	v_add_f32_e32 v209, v130, v131
	v_add_f32_e32 v210, v132, v133
	v_add_f32_e32 v211, v134, v135
	v_add_f32_e32 v212, v136, v137
	v_add_f32_e32 v213, v138, v139
	v_add_f32_e32 v214, v140, v141
	v_add_f32_e32 v215, v142, v143
	v_add_f32_e32 v208, v208, v209
	v_add_f32_e32 v210, v210, v211
	v_add_f32_e32 v212, v212, v213
	v_add_f32_e32 v214, v214, v215
	v_add_f32_e32 v208, v208, v210
	v_add_f32_e32 v212, v212, v214
	v_add_f32_e32 v208, v208, v212
	v_fmamk_f32 v208, v208, 0x3a800000, v21
	v_rsq_f32_e32 v208, v208
	v_lshlrev_b32_e32 v176, 16, v144
	v_and_b32_e32 v177, 0xffff0000, v144
	v_lshlrev_b32_e32 v178, 16, v145
	v_and_b32_e32 v179, 0xffff0000, v145
	v_lshlrev_b32_e32 v180, 16, v146
	v_and_b32_e32 v181, 0xffff0000, v146
	v_lshlrev_b32_e32 v182, 16, v147
	v_and_b32_e32 v183, 0xffff0000, v147
	v_lshlrev_b32_e32 v184, 16, v148
	v_and_b32_e32 v185, 0xffff0000, v148
	v_lshlrev_b32_e32 v186, 16, v149
	v_and_b32_e32 v187, 0xffff0000, v149
	v_lshlrev_b32_e32 v188, 16, v150
	v_and_b32_e32 v189, 0xffff0000, v150
	v_lshlrev_b32_e32 v190, 16, v151
	v_and_b32_e32 v191, 0xffff0000, v151
	v_pk_mul_f32 v[176:177], v[208:209], v[176:177] op_sel_hi:[0,1]
	v_pk_mul_f32 v[178:179], v[208:209], v[178:179] op_sel_hi:[0,1]
	v_pk_mul_f32 v[180:181], v[208:209], v[180:181] op_sel_hi:[0,1]
	v_pk_mul_f32 v[182:183], v[208:209], v[182:183] op_sel_hi:[0,1]
	v_pk_mul_f32 v[184:185], v[208:209], v[184:185] op_sel_hi:[0,1]
	v_pk_mul_f32 v[186:187], v[208:209], v[186:187] op_sel_hi:[0,1]
	v_pk_mul_f32 v[188:189], v[208:209], v[188:189] op_sel_hi:[0,1]
	v_pk_mul_f32 v[190:191], v[208:209], v[190:191] op_sel_hi:[0,1]
	v_pk_mul_f32 v[176:177], v[64:65], v[176:177]
	v_pk_mul_f32 v[178:179], v[66:67], v[178:179]
	v_pk_mul_f32 v[180:181], v[68:69], v[180:181]
	v_pk_mul_f32 v[182:183], v[70:71], v[182:183]
	v_pk_mul_f32 v[184:185], v[72:73], v[184:185]
	v_pk_mul_f32 v[186:187], v[74:75], v[186:187]
	v_pk_mul_f32 v[188:189], v[76:77], v[188:189]
	v_pk_mul_f32 v[190:191], v[78:79], v[190:191]
	global_load_dwordx4 v[128:131], v20, s[0:1]
	global_load_dwordx4 v[132:135], v20, s[0:1] offset:16
	global_load_dwordx4 v[136:139], v20, s[0:1] offset:32
	global_load_dwordx4 v[140:143], v20, s[0:1] offset:48
	global_load_dwordx2 v[144:145], v61, s[22:23]
	global_load_dwordx2 v[146:147], v61, s[22:23] offset:512
	global_load_dwordx2 v[148:149], v61, s[22:23] offset:1024
	global_load_dwordx2 v[150:151], v61, s[22:23] offset:1536
	s_add_u32 s0, s0, s2
	s_addc_u32 s1, s1, s3
	s_add_u32 s22, s22, s6
	s_addc_u32 s23, s23, s7
	global_store_dwordx4 v60, v[176:179], s[24:25]
	global_store_dwordx4 v60, v[180:183], s[24:25] offset:1024
	global_store_dwordx4 v60, v[184:187], s[24:25] offset:2048
	global_store_dwordx4 v60, v[188:191], s[24:25] offset:3072
	s_add_u32 s24, s24, s4
	s_addc_u32 s25, s25, s5
	s_waitcnt vmcnt(40)
	v_add_f32_e32 v208, v152, v153
	v_add_f32_e32 v209, v154, v155
	v_add_f32_e32 v210, v156, v157
	v_add_f32_e32 v211, v158, v159
	v_add_f32_e32 v212, v160, v161
	v_add_f32_e32 v213, v162, v163
	v_add_f32_e32 v214, v164, v165
	v_add_f32_e32 v215, v166, v167
	v_add_f32_e32 v208, v208, v209
	v_add_f32_e32 v210, v210, v211
	v_add_f32_e32 v212, v212, v213
	v_add_f32_e32 v214, v214, v215
	v_add_f32_e32 v208, v208, v210
	v_add_f32_e32 v212, v212, v214
	v_add_f32_e32 v208, v208, v212
	v_fmamk_f32 v208, v208, 0x3a800000, v21
	v_rsq_f32_e32 v208, v208
	v_lshlrev_b32_e32 v192, 16, v168
	v_and_b32_e32 v193, 0xffff0000, v168
	v_lshlrev_b32_e32 v194, 16, v169
	v_and_b32_e32 v195, 0xffff0000, v169
	v_lshlrev_b32_e32 v196, 16, v170
	v_and_b32_e32 v197, 0xffff0000, v170
	v_lshlrev_b32_e32 v198, 16, v171
	v_and_b32_e32 v199, 0xffff0000, v171
	v_lshlrev_b32_e32 v200, 16, v172
	v_and_b32_e32 v201, 0xffff0000, v172
	v_lshlrev_b32_e32 v202, 16, v173
	v_and_b32_e32 v203, 0xffff0000, v173
	v_lshlrev_b32_e32 v204, 16, v174
	v_and_b32_e32 v205, 0xffff0000, v174
	v_lshlrev_b32_e32 v206, 16, v175
	v_and_b32_e32 v207, 0xffff0000, v175
	v_pk_mul_f32 v[192:193], v[208:209], v[192:193] op_sel_hi:[0,1]
	v_pk_mul_f32 v[194:195], v[208:209], v[194:195] op_sel_hi:[0,1]
	v_pk_mul_f32 v[196:197], v[208:209], v[196:197] op_sel_hi:[0,1]
	v_pk_mul_f32 v[198:199], v[208:209], v[198:199] op_sel_hi:[0,1]
	v_pk_mul_f32 v[200:201], v[208:209], v[200:201] op_sel_hi:[0,1]
	v_pk_mul_f32 v[202:203], v[208:209], v[202:203] op_sel_hi:[0,1]
	v_pk_mul_f32 v[204:205], v[208:209], v[204:205] op_sel_hi:[0,1]
	v_pk_mul_f32 v[206:207], v[208:209], v[206:207] op_sel_hi:[0,1]
	v_pk_mul_f32 v[192:193], v[64:65], v[192:193]
	v_pk_mul_f32 v[194:195], v[66:67], v[194:195]
	v_pk_mul_f32 v[196:197], v[68:69], v[196:197]
	v_pk_mul_f32 v[198:199], v[70:71], v[198:199]
	v_pk_mul_f32 v[200:201], v[72:73], v[200:201]
	v_pk_mul_f32 v[202:203], v[74:75], v[202:203]
	v_pk_mul_f32 v[204:205], v[76:77], v[204:205]
	v_pk_mul_f32 v[206:207], v[78:79], v[206:207]
	global_load_dwordx4 v[152:155], v20, s[0:1]
	global_load_dwordx4 v[156:159], v20, s[0:1] offset:16
	global_load_dwordx4 v[160:163], v20, s[0:1] offset:32
	global_load_dwordx4 v[164:167], v20, s[0:1] offset:48
	global_load_dwordx2 v[168:169], v61, s[22:23]
	global_load_dwordx2 v[170:171], v61, s[22:23] offset:512
	global_load_dwordx2 v[172:173], v61, s[22:23] offset:1024
	global_load_dwordx2 v[174:175], v61, s[22:23] offset:1536
	s_add_u32 s0, s0, s2
	s_addc_u32 s1, s1, s3
	s_add_u32 s22, s22, s6
	s_addc_u32 s23, s23, s7
	global_store_dwordx4 v60, v[192:195], s[24:25]
	global_store_dwordx4 v60, v[196:199], s[24:25] offset:1024
	global_store_dwordx4 v60, v[200:203], s[24:25] offset:2048
	global_store_dwordx4 v60, v[204:207], s[24:25] offset:3072
	s_add_u32 s24, s24, s4
	s_addc_u32 s25, s25, s5
	s_waitcnt vmcnt(40)
	v_add_f32_e32 v208, v80, v81
	v_add_f32_e32 v209, v82, v83
	v_add_f32_e32 v210, v84, v85
	v_add_f32_e32 v211, v86, v87
	v_add_f32_e32 v212, v88, v89
	v_add_f32_e32 v213, v90, v91
	v_add_f32_e32 v214, v92, v93
	v_add_f32_e32 v215, v94, v95
	v_add_f32_e32 v208, v208, v209
	v_add_f32_e32 v210, v210, v211
	v_add_f32_e32 v212, v212, v213
	v_add_f32_e32 v214, v214, v215
	v_add_f32_e32 v208, v208, v210
	v_add_f32_e32 v212, v212, v214
	v_add_f32_e32 v208, v208, v212
	v_fmamk_f32 v208, v208, 0x3a800000, v21
	v_rsq_f32_e32 v208, v208
	v_lshlrev_b32_e32 v176, 16, v96
	v_and_b32_e32 v177, 0xffff0000, v96
	v_lshlrev_b32_e32 v178, 16, v97
	v_and_b32_e32 v179, 0xffff0000, v97
	v_lshlrev_b32_e32 v180, 16, v98
	v_and_b32_e32 v181, 0xffff0000, v98
	v_lshlrev_b32_e32 v182, 16, v99
	v_and_b32_e32 v183, 0xffff0000, v99
	v_lshlrev_b32_e32 v184, 16, v100
	v_and_b32_e32 v185, 0xffff0000, v100
	v_lshlrev_b32_e32 v186, 16, v101
	v_and_b32_e32 v187, 0xffff0000, v101
	v_lshlrev_b32_e32 v188, 16, v102
	v_and_b32_e32 v189, 0xffff0000, v102
	v_lshlrev_b32_e32 v190, 16, v103
	v_and_b32_e32 v191, 0xffff0000, v103
	v_pk_mul_f32 v[176:177], v[208:209], v[176:177] op_sel_hi:[0,1]
	v_pk_mul_f32 v[178:179], v[208:209], v[178:179] op_sel_hi:[0,1]
	v_pk_mul_f32 v[180:181], v[208:209], v[180:181] op_sel_hi:[0,1]
	v_pk_mul_f32 v[182:183], v[208:209], v[182:183] op_sel_hi:[0,1]
	v_pk_mul_f32 v[184:185], v[208:209], v[184:185] op_sel_hi:[0,1]
	v_pk_mul_f32 v[186:187], v[208:209], v[186:187] op_sel_hi:[0,1]
	v_pk_mul_f32 v[188:189], v[208:209], v[188:189] op_sel_hi:[0,1]
	v_pk_mul_f32 v[190:191], v[208:209], v[190:191] op_sel_hi:[0,1]
	v_pk_mul_f32 v[176:177], v[64:65], v[176:177]
	v_pk_mul_f32 v[178:179], v[66:67], v[178:179]
	v_pk_mul_f32 v[180:181], v[68:69], v[180:181]
	v_pk_mul_f32 v[182:183], v[70:71], v[182:183]
	v_pk_mul_f32 v[184:185], v[72:73], v[184:185]
	v_pk_mul_f32 v[186:187], v[74:75], v[186:187]
	v_pk_mul_f32 v[188:189], v[76:77], v[188:189]
	v_pk_mul_f32 v[190:191], v[78:79], v[190:191]
	global_store_dwordx4 v60, v[176:179], s[24:25]
	global_store_dwordx4 v60, v[180:183], s[24:25] offset:1024
	global_store_dwordx4 v60, v[184:187], s[24:25] offset:2048
	global_store_dwordx4 v60, v[188:191], s[24:25] offset:3072
	s_add_u32 s24, s24, s4
	s_addc_u32 s25, s25, s5
	s_waitcnt vmcnt(32)
	v_add_f32_e32 v208, v104, v105
	v_add_f32_e32 v209, v106, v107
	v_add_f32_e32 v210, v108, v109
	v_add_f32_e32 v211, v110, v111
	v_add_f32_e32 v212, v112, v113
	v_add_f32_e32 v213, v114, v115
	v_add_f32_e32 v214, v116, v117
	v_add_f32_e32 v215, v118, v119
	v_add_f32_e32 v208, v208, v209
	v_add_f32_e32 v210, v210, v211
	v_add_f32_e32 v212, v212, v213
	v_add_f32_e32 v214, v214, v215
	v_add_f32_e32 v208, v208, v210
	v_add_f32_e32 v212, v212, v214
	v_add_f32_e32 v208, v208, v212
	v_fmamk_f32 v208, v208, 0x3a800000, v21
	v_rsq_f32_e32 v208, v208
	v_lshlrev_b32_e32 v192, 16, v120
	v_and_b32_e32 v193, 0xffff0000, v120
	v_lshlrev_b32_e32 v194, 16, v121
	v_and_b32_e32 v195, 0xffff0000, v121
	v_lshlrev_b32_e32 v196, 16, v122
	v_and_b32_e32 v197, 0xffff0000, v122
	v_lshlrev_b32_e32 v198, 16, v123
	v_and_b32_e32 v199, 0xffff0000, v123
	v_lshlrev_b32_e32 v200, 16, v124
	v_and_b32_e32 v201, 0xffff0000, v124
	v_lshlrev_b32_e32 v202, 16, v125
	v_and_b32_e32 v203, 0xffff0000, v125
	v_lshlrev_b32_e32 v204, 16, v126
	v_and_b32_e32 v205, 0xffff0000, v126
	v_lshlrev_b32_e32 v206, 16, v127
	v_and_b32_e32 v207, 0xffff0000, v127
	v_pk_mul_f32 v[192:193], v[208:209], v[192:193] op_sel_hi:[0,1]
	v_pk_mul_f32 v[194:195], v[208:209], v[194:195] op_sel_hi:[0,1]
	v_pk_mul_f32 v[196:197], v[208:209], v[196:197] op_sel_hi:[0,1]
	v_pk_mul_f32 v[198:199], v[208:209], v[198:199] op_sel_hi:[0,1]
	v_pk_mul_f32 v[200:201], v[208:209], v[200:201] op_sel_hi:[0,1]
	v_pk_mul_f32 v[202:203], v[208:209], v[202:203] op_sel_hi:[0,1]
	v_pk_mul_f32 v[204:205], v[208:209], v[204:205] op_sel_hi:[0,1]
	v_pk_mul_f32 v[206:207], v[208:209], v[206:207] op_sel_hi:[0,1]
	v_pk_mul_f32 v[192:193], v[64:65], v[192:193]
	v_pk_mul_f32 v[194:195], v[66:67], v[194:195]
	v_pk_mul_f32 v[196:197], v[68:69], v[196:197]
	v_pk_mul_f32 v[198:199], v[70:71], v[198:199]
	v_pk_mul_f32 v[200:201], v[72:73], v[200:201]
	v_pk_mul_f32 v[202:203], v[74:75], v[202:203]
	v_pk_mul_f32 v[204:205], v[76:77], v[204:205]
	v_pk_mul_f32 v[206:207], v[78:79], v[206:207]
	global_store_dwordx4 v60, v[192:195], s[24:25]
	global_store_dwordx4 v60, v[196:199], s[24:25] offset:1024
	global_store_dwordx4 v60, v[200:203], s[24:25] offset:2048
	global_store_dwordx4 v60, v[204:207], s[24:25] offset:3072
	s_add_u32 s24, s24, s4
	s_addc_u32 s25, s25, s5
	s_waitcnt vmcnt(24)
	v_add_f32_e32 v208, v128, v129
	v_add_f32_e32 v209, v130, v131
	v_add_f32_e32 v210, v132, v133
	v_add_f32_e32 v211, v134, v135
	v_add_f32_e32 v212, v136, v137
	v_add_f32_e32 v213, v138, v139
	v_add_f32_e32 v214, v140, v141
	v_add_f32_e32 v215, v142, v143
	v_add_f32_e32 v208, v208, v209
	v_add_f32_e32 v210, v210, v211
	v_add_f32_e32 v212, v212, v213
	v_add_f32_e32 v214, v214, v215
	v_add_f32_e32 v208, v208, v210
	v_add_f32_e32 v212, v212, v214
	v_add_f32_e32 v208, v208, v212
	v_fmamk_f32 v208, v208, 0x3a800000, v21
	v_rsq_f32_e32 v208, v208
	v_lshlrev_b32_e32 v176, 16, v144
	v_and_b32_e32 v177, 0xffff0000, v144
	v_lshlrev_b32_e32 v178, 16, v145
	v_and_b32_e32 v179, 0xffff0000, v145
	v_lshlrev_b32_e32 v180, 16, v146
	v_and_b32_e32 v181, 0xffff0000, v146
	v_lshlrev_b32_e32 v182, 16, v147
	v_and_b32_e32 v183, 0xffff0000, v147
	v_lshlrev_b32_e32 v184, 16, v148
	v_and_b32_e32 v185, 0xffff0000, v148
	v_lshlrev_b32_e32 v186, 16, v149
	v_and_b32_e32 v187, 0xffff0000, v149
	v_lshlrev_b32_e32 v188, 16, v150
	v_and_b32_e32 v189, 0xffff0000, v150
	v_lshlrev_b32_e32 v190, 16, v151
	v_and_b32_e32 v191, 0xffff0000, v151
	v_pk_mul_f32 v[176:177], v[208:209], v[176:177] op_sel_hi:[0,1]
	v_pk_mul_f32 v[178:179], v[208:209], v[178:179] op_sel_hi:[0,1]
	v_pk_mul_f32 v[180:181], v[208:209], v[180:181] op_sel_hi:[0,1]
	v_pk_mul_f32 v[182:183], v[208:209], v[182:183] op_sel_hi:[0,1]
	v_pk_mul_f32 v[184:185], v[208:209], v[184:185] op_sel_hi:[0,1]
	v_pk_mul_f32 v[186:187], v[208:209], v[186:187] op_sel_hi:[0,1]
	v_pk_mul_f32 v[188:189], v[208:209], v[188:189] op_sel_hi:[0,1]
	v_pk_mul_f32 v[190:191], v[208:209], v[190:191] op_sel_hi:[0,1]
	v_pk_mul_f32 v[176:177], v[64:65], v[176:177]
	v_pk_mul_f32 v[178:179], v[66:67], v[178:179]
	v_pk_mul_f32 v[180:181], v[68:69], v[180:181]
	v_pk_mul_f32 v[182:183], v[70:71], v[182:183]
	v_pk_mul_f32 v[184:185], v[72:73], v[184:185]
	v_pk_mul_f32 v[186:187], v[74:75], v[186:187]
	v_pk_mul_f32 v[188:189], v[76:77], v[188:189]
	v_pk_mul_f32 v[190:191], v[78:79], v[190:191]
	global_store_dwordx4 v60, v[176:179], s[24:25]
	global_store_dwordx4 v60, v[180:183], s[24:25] offset:1024
	global_store_dwordx4 v60, v[184:187], s[24:25] offset:2048
	global_store_dwordx4 v60, v[188:191], s[24:25] offset:3072
	s_add_u32 s24, s24, s4
	s_addc_u32 s25, s25, s5
	s_waitcnt vmcnt(16)
	v_add_f32_e32 v208, v152, v153
	v_add_f32_e32 v209, v154, v155
	v_add_f32_e32 v210, v156, v157
	v_add_f32_e32 v211, v158, v159
	v_add_f32_e32 v212, v160, v161
	v_add_f32_e32 v213, v162, v163
	v_add_f32_e32 v214, v164, v165
	v_add_f32_e32 v215, v166, v167
	v_add_f32_e32 v208, v208, v209
	v_add_f32_e32 v210, v210, v211
	v_add_f32_e32 v212, v212, v213
	v_add_f32_e32 v214, v214, v215
	v_add_f32_e32 v208, v208, v210
	v_add_f32_e32 v212, v212, v214
	v_add_f32_e32 v208, v208, v212
	v_fmamk_f32 v208, v208, 0x3a800000, v21
	v_rsq_f32_e32 v208, v208
	v_lshlrev_b32_e32 v192, 16, v168
	v_and_b32_e32 v193, 0xffff0000, v168
	v_lshlrev_b32_e32 v194, 16, v169
	v_and_b32_e32 v195, 0xffff0000, v169
	v_lshlrev_b32_e32 v196, 16, v170
	v_and_b32_e32 v197, 0xffff0000, v170
	v_lshlrev_b32_e32 v198, 16, v171
	v_and_b32_e32 v199, 0xffff0000, v171
	v_lshlrev_b32_e32 v200, 16, v172
	v_and_b32_e32 v201, 0xffff0000, v172
	v_lshlrev_b32_e32 v202, 16, v173
	v_and_b32_e32 v203, 0xffff0000, v173
	v_lshlrev_b32_e32 v204, 16, v174
	v_and_b32_e32 v205, 0xffff0000, v174
	v_lshlrev_b32_e32 v206, 16, v175
	v_and_b32_e32 v207, 0xffff0000, v175
	v_pk_mul_f32 v[192:193], v[208:209], v[192:193] op_sel_hi:[0,1]
	v_pk_mul_f32 v[194:195], v[208:209], v[194:195] op_sel_hi:[0,1]
	v_pk_mul_f32 v[196:197], v[208:209], v[196:197] op_sel_hi:[0,1]
	v_pk_mul_f32 v[198:199], v[208:209], v[198:199] op_sel_hi:[0,1]
	v_pk_mul_f32 v[200:201], v[208:209], v[200:201] op_sel_hi:[0,1]
	v_pk_mul_f32 v[202:203], v[208:209], v[202:203] op_sel_hi:[0,1]
	v_pk_mul_f32 v[204:205], v[208:209], v[204:205] op_sel_hi:[0,1]
	v_pk_mul_f32 v[206:207], v[208:209], v[206:207] op_sel_hi:[0,1]
	v_pk_mul_f32 v[192:193], v[64:65], v[192:193]
	v_pk_mul_f32 v[194:195], v[66:67], v[194:195]
	v_pk_mul_f32 v[196:197], v[68:69], v[196:197]
	v_pk_mul_f32 v[198:199], v[70:71], v[198:199]
	v_pk_mul_f32 v[200:201], v[72:73], v[200:201]
	v_pk_mul_f32 v[202:203], v[74:75], v[202:203]
	v_pk_mul_f32 v[204:205], v[76:77], v[204:205]
	v_pk_mul_f32 v[206:207], v[78:79], v[206:207]
	global_store_dwordx4 v60, v[192:195], s[24:25]
	global_store_dwordx4 v60, v[196:199], s[24:25] offset:1024
	global_store_dwordx4 v60, v[200:203], s[24:25] offset:2048
	global_store_dwordx4 v60, v[204:207], s[24:25] offset:3072
	s_add_u32 s24, s24, s4
	s_addc_u32 s25, s25, s5
	s_endpgm
